# in-proj: second-round tile assignment rotated by 5 within the XCD so a CU never gets two heavy-epilogue tiles (rope / cache-output column tiles)
# speedup vs baseline: 1.0109x; 1.0047x over previous
.LBB0_463:
	s_add_i32 s63, s63, 1
	s_mul_i32 s1, s63, s51
	s_mul_hi_u32 s4, s63, s42
	s_add_i32 s4, s4, s1
	s_mul_i32 s1, s63, s42
	s_add_u32 s56, s1, s2
	s_addc_u32 s57, s4, s43
	v_mov_b64_e32 v[0:1], 0x200
	v_cmp_lt_i64_e64 s[4:5], s[56:57], v[0:1]
	v_mov_b64_e32 v[0:1], 0x1ff
	v_cmp_gt_i64_e32 vcc, s[56:57], v[0:1]
	s_cbranch_vccnz .LBB0_468
	s_and_b32 s1, s56, 7
	s_lshr_b32 s13, s56, 3
	s_add_i32 s13, s13, 5
	s_and_b32 s13, s13, 31
	s_or_b32 s13, s13, 32
	s_cmp_lt_u32 s13, 20
	s_cbranch_scc0 .Lmy_in_lat
	s_cmp_ge_u32 s13, 10
	s_cselect_b32 s22, 1, 0
	s_mul_i32 s24, s22, 10
	s_sub_i32 s24, s13, s24
	s_lshl_b32 s1, s1, 1
	s_add_i32 s22, s22, s1
	s_cmp_gt_u32 s24, 7
	s_addc_u32 s24, s24, 0
	s_branch .LBB0_468
